# longer poll intervals at every spin site (dataflow/global counters s_sleep 8, group barriers s_sleep 3, pair barrier s_sleep 12)
# baseline (speedup 1.0000x reference)
; template <class Epi, class Sched, bool ALIGN_EPI = false, bool SP2 = false, bool SPLITK = false>
; __device__ __forceinline__ void gemm_phase(PG8_LAS unsigned char* lds, const Gemm g, const Sched& S, const Epi& E) {
;     ...
;         const bool has_next = S.next(ui + 1, nxt);
;         const char* nA = has_next ? (const char*)g.A + (size_t)nxt.pm * tstep : cA; const char* nB = has_next ? (const char*)g.Bt + (size_t)nxt.pn * tstep : cB;
;         for (int t = 0; t < nt; t += 2) {
;             const bool last = (t == nt - 2);
;             if constexpr (SPLITK) { if (t == nt1) E.mid(acc, cur, wr, wc, fr, fq); }
;             const char* a1 = PG8_TA(t + 1);
;             const char* a2 = last ? nA : PG8_TA(t + 2); const char* b2 = last ? nB : PG8_TB(t + 2);
;             const char* a3 = a2 + kstep; const char* b3 = b2 + kstep;
;             if (last && has_next) S.a_ready(nxt);
.Lgb_p6_spin:
	global_load_dword v131, v130, s[100:101] sc1
	s_waitcnt vmcnt(0)
	v_readfirstlane_b32 s4, v131
	s_nop 3
	s_lshr_b32 s4, s4, 8
	s_cmp_ge_u32 s4, s92
	s_cbranch_scc1 .Lgb_p6_ok
	s_sleep 8
	s_add_i32 vcc_lo, vcc_lo, 1
	s_cmp_lt_u32 vcc_lo, 0x40000
	s_cbranch_scc1 .Lgb_p6_spin

; __global__ void __launch_bounds__(NWAVES * 64, 2) mk_fwd(Args a) {
;     ...
;             int vcup = vcu; asm volatile("" : "+s"(vcup));
;             const float lam = lamtab[l], osc = 1.0f - a.linit[l];
;             const float* sw = subln_w + l * 128;
;             const int convslot = (G == 256) ? (vcup & 3) : 0; int ucount = 0; bool conv_done = false;
; #pragma unroll 1
;             for (int gidx = vcup; gidx < 512; gidx += G) {
;                 const int gi = gidx >> 8, v = gidx & 255, bh = v >> 3, s = v & 7, qb = gi ? 15 - s : s, b = bh >> 3, h = bh & 7;
; #pragma unroll 1
;                 for (int m = 0; m < 2; ++m) {
;                     if (ucount == convslot) { conv_items(BGb, CGb, conv_w + (size_t)l * 3 * DMOD, vcup, G); conv_done = true; }
;                     ++ucount;
;                     attn_body::attn_unit<8>(b, 2 * h + m, 128 * h, qb, (const attn_body::bf16*)Qb, (const attn_body::bf16*)Kb, (const attn_body::bf16*)Vb, (attn_body::bf16*)(m ? O2 : O1), (char*)lds);
.Lflow_spin_403:
	global_load_dword v6, v5, s[12:13] sc1
	s_waitcnt vmcnt(0)
	v_readfirstlane_b32 s4, v6
	s_nop 3
	s_cmp_ge_u32 s4, s21
	s_cbranch_scc1 .Lflow_done_403
	s_sleep 8
	s_add_i32 s1, s1, 1
	s_cmp_lt_u32 s1, 0x40000
	s_cbranch_scc1 .Lflow_spin_403

; __device__ __forceinline__ unsigned xb_ld(unsigned* p)              { return __hip_atomic_load(p, __ATOMIC_RELAXED, __HIP_MEMORY_SCOPE_AGENT); }
; __device__ __forceinline__ unsigned xb_add(unsigned* p, unsigned v) { return __hip_atomic_fetch_add(p, v, __ATOMIC_RELAXED, __HIP_MEMORY_SCOPE_AGENT); }
; #define XB_SPIN(cond, bar) do { unsigned _sp = 0; while (cond) { __builtin_amdgcn_s_sleep(1); \
;     if ((++_sp & 255u) == 0u) { if (xb_ld(&(bar)[XB_TMO])) break; if (_sp > XB_SPIN_CAP) { atomicAdd(&(bar)[XB_TMO], 1u); break; } } } } while (0)
; __device__ __forceinline__ void xcd_barrier(const XcdBarrier& b) {
;     asm volatile("s_waitcnt vmcnt(0)" ::: "memory");
;     __syncthreads();
;     if (threadIdx.x == 0) {
;         unsigned* bar = b.bar;
;         __builtin_amdgcn_s_waitcnt(0);
;         unsigned nloc = b.st[0], nx = b.st[1];
;         if (nloc == 0u) { xcd_barrier_complete(bar, b.x, nloc, nx); b.st[0] = nloc; b.st[1] = nx; }
;         const unsigned old = xb_add(&bar[XB_XSUB(b.x)], 1u);
;         const unsigned gen = old / nloc;
;         if (old + 1u == (gen + 1u) * nloc) {
;             __builtin_amdgcn_fence(__ATOMIC_RELEASE, "agent");
;             asm volatile("s_waitcnt vmcnt(0)" ::: "memory");
;             const unsigned og = xb_add(&bar[XB_TOP], 1u);
;             const unsigned tg = og / nx;
;             if (og + 1u == (tg + 1u) * nx) xb_add(&bar[XB_TOPGEN], 1u);
;             else XB_SPIN(xb_ld(&bar[XB_TOPGEN]) == tg, bar);
;             __builtin_amdgcn_fence(__ATOMIC_ACQUIRE, "agent");
;             xb_add(&bar[XB_XGEN(b.x)], 1u);
;             asm volatile("s_waitcnt vmcnt(0)" ::: "memory");
;         } else {
;             XB_SPIN(xb_ld(&bar[XB_XGEN(b.x)]) == gen, bar);
;             __builtin_amdgcn_fence(__ATOMIC_ACQUIRE, "agent");
;             asm volatile("s_waitcnt vmcnt(0)" ::: "memory");
;         }
;     }
;     __syncthreads();
; }
.Lgb_grp_493:
	global_load_dword v3, v2, s[12:13] sc1
	s_waitcnt vmcnt(0)
	v_readfirstlane_b32 s4, v3
	s_nop 3
	s_cmp_ge_u32 s4, s99
	s_cbranch_scc1 .Lgb_grp_ok_493
	s_sleep 3
	s_add_i32 s1, s1, 1
	s_cmp_lt_u32 s1, 0x40000
	s_cbranch_scc1 .Lgb_grp_493

; #define GSYNC() do { for (int r_ = 0; r_ < REP_SYNC; ++r_) xcd_barrier(bar); } while (0)
; __global__ void __launch_bounds__(NWAVES * 64, 2) mk_fwd(Args a) {
;     ...
;         GSYNC();
; #pragma unroll 1
;         for (int rep3 = 0; rep3 < REP_P3; ++rep3) {
;             int bxp = bx; asm volatile("" : "+s"(bxp)); pg8::StaticOrder S; S.init(NTOK, DMOD, G, bxp);
;             pg8::Gemm g{Qb, (const bf16u*)(wl + WL_A), NTOK, DMOD, DMOD, BGb, (const bf16u*)(wl + WL_B)}; pg8::EpiMix2 E{SGA, SGB, MIXED};
;             pg8::gemm_phase<pg8::EpiMix2, pg8::StaticOrder, true, true, true>(L, g, S, E);
.Lgb_p3_569:
	global_load_dword v3, v4, s[12:13] sc1
	s_waitcnt vmcnt(0)
	v_readfirstlane_b32 s17, v3
	s_nop 3
	s_cmp_ge_u32 s17, s16
	s_cbranch_scc1 .Lgb_p3_ok_569
	s_sleep 8
	s_add_i32 s1, s1, 1
	s_cmp_lt_u32 s1, 0x40000
	s_cbranch_scc1 .Lgb_p3_569

; __global__ void __launch_bounds__(NWAVES * 64, 2) mk_fwd(Args a) {
;     ...
;             if (l + 1 < NLAYER && rep5 == 0) {
;                 const int nwg5 = (NTOK / 256) * (2 * DFF / 256), rem = nwg5 % G;
;                 const bool light = (rem == 0) || (bxp >= rem);
;                 if (light) { int tc_ = threadIdx.x; asm volatile("" : "+v"(tc_)); const int lnc = tc_ & 63; const int nl = (rem == 0) ? G : G - rem, li = (rem == 0) ? bxp : bxp - rem;
;                     CONVERT_LAYER(l + 1, li * NWAVES + wave, nl * NWAVES, lnc); }
.Lgb_cv_137:
	global_load_dword v3, v4, s[12:13] sc1
	s_waitcnt vmcnt(0)
	v_readfirstlane_b32 s19, v3
	s_nop 3
	s_cmp_ge_u32 s19, s18
	s_cbranch_scc1 .Lgb_cv_ok_137
	s_sleep 8
	s_add_i32 s1, s1, 1
	s_cmp_lt_u32 s1, 0x40000
	s_cbranch_scc1 .Lgb_cv_137
